# v14 + P0: leftover hx row groups given to all 8 waves of the 64 workgroups without mod-GEMV columns instead of waves 0-1 of every workgroup
# speedup vs baseline: 1.0010x; 1.0002x over previous
.LBB0_152:
	s_or_b64 exec, exec, s[8:9]
	s_abs_i32 s8, s33
	v_cvt_f32_u32_e32 v1, s8
	s_sub_i32 s10, 0, s8
	s_ashr_i32 s9, s33, 31
	v_rcp_iflag_f32_e32 v1, v1
	s_nop 0
	v_mul_f32_e32 v1, 0x4f7ffffe, v1
	v_cvt_u32_f32_e32 v1, v1
	s_nop 0
	v_readfirstlane_b32 s11, v1
	s_mul_i32 s10, s10, s11
	s_mul_hi_u32 s10, s11, s10
	s_add_i32 s11, s11, s10
	s_mul_hi_u32 s10, s11, 0x1200
	s_mul_i32 s11, s10, s8
	s_sub_i32 s11, 0x1200, s11
	s_add_i32 s12, s10, 1
	s_sub_i32 s13, s11, s8
	s_cmp_ge_u32 s11, s8
	s_cselect_b32 s10, s12, s10
	s_cselect_b32 s11, s13, s11
	s_add_i32 s12, s10, 1
	s_cmp_ge_u32 s11, s8
	s_cselect_b32 s8, s12, s10
	s_xor_b32 s8, s8, s9
	s_sub_i32 s38, s8, s9
	s_cmp_lt_i32 s38, 0
	s_mov_b32 s13, 0
	s_cbranch_scc1 .LBB0_195
	s_load_dwordx16 s[16:31], s[0:1], 0xc0
	s_mul_i32 s10, s38, s33
	s_sub_i32 s11, 0x1200, s10
	v_mov_b32_e32 v71, 0
	s_waitcnt vmcnt(7)
	v_lshlrev_b32_e32 v2, 3, v178
	s_waitcnt lgkmcnt(0)
	s_add_u32 s8, s30, 0x5c00000
	s_addc_u32 s9, s31, 0
	s_add_u32 s14, s30, 0xdc00000
	s_addc_u32 s15, s31, 0
	v_mov_b32_e32 v3, v71
	v_lshlrev_b32_e32 v70, 2, v178
	v_lshl_add_u64 v[72:73], s[14:15], 0, v[2:3]
	v_readlane_b32 s12, v252, 39
	v_lshlrev_b32_e32 v2, 4, v178
	v_or_b32_e32 v78, 0x200, v70
	v_mov_b32_e32 v79, v71
	s_sub_i32 s39, s96, 0xc0
	v_lshl_add_u64 v[82:83], s[80:81], 0, v[2:3]
	v_mbcnt_lo_u32_b32 v2, -1, 0
	s_lshl_b32 s39, s39, 3
	s_add_i32 s39, s39, s12
	v_lshl_add_u64 v[86:87], s[8:9], 0, v[78:79]
	v_mbcnt_hi_u32_b32 v79, -1, v2
	v_or_b32_e32 v76, 0x100, v70
	v_mov_b32_e32 v77, v71
	v_or_b32_e32 v80, 0x300, v70
	v_mov_b32_e32 v81, v71
	s_cmp_lt_u32 s39, s11
	v_and_b32_e32 v2, 64, v79
	v_lshl_add_u64 v[74:75], s[8:9], 0, v[70:71]
	s_cselect_b64 s[16:17], -1, 0
	s_add_i32 s39, s39, s10
	v_lshl_add_u64 v[84:85], s[8:9], 0, v[76:77]
	v_lshl_add_u64 v[88:89], s[8:9], 0, v[80:81]
	s_add_i32 s42, s38, 1
	s_movk_i32 s43, 0x1000
	v_lshlrev_b32_e32 v70, 2, v70
	s_movk_i32 s44, 0x2000
	s_movk_i32 s45, 0x3000
	v_mov_b32_e32 v1, 0x358637bd
	s_mov_b32 s46, 0xf800000
	v_mov_b32_e32 v77, 0x260
	v_add_u32_e32 v81, 64, v2
	v_xor_b32_e32 v96, 1, v79
	v_xor_b32_e32 v97, 2, v79
	v_xor_b32_e32 v98, 4, v79
	v_xor_b32_e32 v99, 8, v79
	v_xor_b32_e32 v100, 16, v79
	v_xor_b32_e32 v101, 32, v79
	s_mov_b32 s47, 0
	s_mov_b32 s22, s85
	s_branch .LBB0_155
